# speedup vs baseline: 1.0526x; 1.0108x over previous
; DI unsigned cvtpk(float lo, float hi) { unsigned r; asm volatile("v_cvt_pk_bf16_f32 %0, %1, %2" : "=v"(r) : "v"(lo), "v"(hi)); return r; }
; DI int crow(int r, int hi) { return (r & 3) + 8 * (r >> 2) + 4 * hi; }
; DI float shx1(float v) { return __int_as_float(__builtin_amdgcn_mov_dpp(__float_as_int(v), 0xB1, 0xf, 0xf, true)); }
; #define SBAR() __builtin_amdgcn_sched_barrier(0)
; #define VMWN(n) asm volatile("s_waitcnt vmcnt(%0)" :: "i"(n) : "memory")
; #define SWRITE_HK(bf, cr) do { *(bf16x8*)(K_lds + (bf) * SHM_K + kws) = S.st_k0; *(bf16x8*)(K_lds + (bf) * SHM_K + kws + 32 * 256) = S.st_k1; \
;                          if (tid < 64) bias[(bf) * 64 + tid] = ((cr) - S.st_c) * INV_SCALE; } while (0)
; DI int block(const PP& p, const ARef& cur, volatile int* slot, unsigned* ctr, int base, int total, char* lds, Seam& S, bool dummy, const unsigned* nrm) {
;     ...
;     SBAR(); VMWN(8); SWRITE_HK(0, crn); SBAR();
;     S.cref = crn;
;     if (hi == 0) li_l[r32] = l_reg; asm volatile("s_waitcnt lgkmcnt(0)" ::: "memory");
;     float rli[16];
; #pragma unroll
;     for (int r = 0; r < 16; ++r) rli[r] = __builtin_amdgcn_rcpf(li_l[crow(r, hi)]);
;     bf16_t* Ow = cur.O + (size_t)(wid * QBLK) * cur.ldo;
; #pragma unroll
;     for (int r = 0; r < 16; ++r) { const int orow = crow(r, hi);
; #pragma unroll
;         for (int d0 = 0; d0 < 4; ++d0) { const float v = o[d0][r] * rli[r];
;             const float vn = shx1(v);
;             if ((r32 & 1) == 0) *(unsigned*)(Ow + (size_t)orow * cur.ldo + d0 * 32 + r32) = cvtpk(v, vn); } }
;     __syncthreads();
;     return Ln;
.Lfa_spin_done:
	global_load_dwordx2 v[68:69], v67, s[14:15] sc0 sc1
	global_load_dwordx4 v[164:167], v66, s[12:13] offset:0 sc0 sc1
	global_load_dwordx4 v[168:171], v66, s[12:13] offset:1024 sc0 sc1
	global_load_dwordx4 v[172:175], v66, s[12:13] offset:2048 sc0 sc1
	global_load_dwordx4 v[176:179], v66, s[12:13] offset:3072 sc0 sc1
	s_add_u32 s12, s12, 0x1000
	s_addc_u32 s13, s13, 0
	global_load_dwordx4 v[180:183], v66, s[12:13] offset:0 sc0 sc1
	global_load_dwordx4 v[184:187], v66, s[12:13] offset:1024 sc0 sc1
	global_load_dwordx4 v[188:191], v66, s[12:13] offset:2048 sc0 sc1
	global_load_dwordx4 v[192:195], v66, s[12:13] offset:3072 sc0 sc1
	s_add_u32 s12, s12, 0x1000
	s_addc_u32 s13, s13, 0
	s_waitcnt vmcnt(8)
	v_max_f32_e32 v70, v196, v68
	v_sub_f32_e32 v71, v196, v70
	v_mul_f32_e32 v71, 0x3e0293ee, v71
	v_exp_f32_e32 v71, v71
	v_sub_f32_e32 v72, v68, v70
	v_mul_f32_e32 v72, 0x3e0293ee, v72
	v_exp_f32_e32 v72, v72
	v_mov_b32_e32 v196, v70
	v_mul_f32_e32 v0, v0, v71
	v_fmac_f32_e32 v0, v69, v72
	v_cmp_gt_u32_e32 vcc, 32, v221
	s_and_saveexec_b64 s[38:39], vcc
	ds_write_b32 v226, v71
	ds_write_b32 v226, v72 offset:128
	s_or_b64 exec, exec, s[38:39]
	s_waitcnt lgkmcnt(0)
	ds_read_b128 v[82:85], v225
	ds_read_b128 v[86:89], v225 offset:32
	ds_read_b128 v[90:93], v225 offset:64
	ds_read_b128 v[94:97], v225 offset:96
	ds_read_b128 v[106:109], v225 offset:128
	ds_read_b128 v[110:113], v225 offset:160
	ds_read_b128 v[114:117], v225 offset:192
	ds_read_b128 v[118:121], v225 offset:224
	s_waitcnt lgkmcnt(0)
	s_waitcnt vmcnt(4)
	v_pk_mul_f32 v[50:51], v[50:51], v[82:83]
	v_pk_fma_f32 v[50:51], v[164:165], v[106:107], v[50:51]
	v_pk_mul_f32 v[52:53], v[52:53], v[84:85]
	v_pk_fma_f32 v[52:53], v[166:167], v[108:109], v[52:53]
	v_pk_mul_f32 v[54:55], v[54:55], v[86:87]
	v_pk_fma_f32 v[54:55], v[168:169], v[110:111], v[54:55]
	v_pk_mul_f32 v[56:57], v[56:57], v[88:89]
	v_pk_fma_f32 v[56:57], v[170:171], v[112:113], v[56:57]
	v_pk_mul_f32 v[58:59], v[58:59], v[90:91]
	v_pk_fma_f32 v[58:59], v[172:173], v[114:115], v[58:59]
	v_pk_mul_f32 v[60:61], v[60:61], v[92:93]
	v_pk_fma_f32 v[60:61], v[174:175], v[116:117], v[60:61]
	v_pk_mul_f32 v[62:63], v[62:63], v[94:95]
	v_pk_fma_f32 v[62:63], v[176:177], v[118:119], v[62:63]
	v_pk_mul_f32 v[64:65], v[64:65], v[96:97]
	v_pk_fma_f32 v[64:65], v[178:179], v[120:121], v[64:65]
	s_waitcnt vmcnt(0)
	v_pk_mul_f32 v[34:35], v[34:35], v[82:83]
	v_pk_fma_f32 v[34:35], v[180:181], v[106:107], v[34:35]
	v_pk_mul_f32 v[36:37], v[36:37], v[84:85]
	v_pk_fma_f32 v[36:37], v[182:183], v[108:109], v[36:37]
	v_pk_mul_f32 v[38:39], v[38:39], v[86:87]
	v_pk_fma_f32 v[38:39], v[184:185], v[110:111], v[38:39]
	v_pk_mul_f32 v[40:41], v[40:41], v[88:89]
	v_pk_fma_f32 v[40:41], v[186:187], v[112:113], v[40:41]
	v_pk_mul_f32 v[42:43], v[42:43], v[90:91]
	v_pk_fma_f32 v[42:43], v[188:189], v[114:115], v[42:43]
	v_pk_mul_f32 v[44:45], v[44:45], v[92:93]
	v_pk_fma_f32 v[44:45], v[190:191], v[116:117], v[44:45]
	v_pk_mul_f32 v[46:47], v[46:47], v[94:95]
	v_pk_fma_f32 v[46:47], v[192:193], v[118:119], v[46:47]
	v_pk_mul_f32 v[48:49], v[48:49], v[96:97]
	v_pk_fma_f32 v[48:49], v[194:195], v[120:121], v[48:49]
	global_load_dwordx4 v[164:167], v66, s[12:13] offset:0 sc0 sc1
	global_load_dwordx4 v[168:171], v66, s[12:13] offset:1024 sc0 sc1
	global_load_dwordx4 v[172:175], v66, s[12:13] offset:2048 sc0 sc1
	global_load_dwordx4 v[176:179], v66, s[12:13] offset:3072 sc0 sc1
	s_add_u32 s12, s12, 0x1000
	s_addc_u32 s13, s13, 0
	global_load_dwordx4 v[180:183], v66, s[12:13] offset:0 sc0 sc1
	global_load_dwordx4 v[184:187], v66, s[12:13] offset:1024 sc0 sc1
	global_load_dwordx4 v[188:191], v66, s[12:13] offset:2048 sc0 sc1
	global_load_dwordx4 v[192:195], v66, s[12:13] offset:3072 sc0 sc1
	s_add_u32 s12, s12, 0x1000
	s_addc_u32 s13, s13, 0
	s_waitcnt vmcnt(4)
	v_pk_mul_f32 v[18:19], v[18:19], v[82:83]
	v_pk_fma_f32 v[18:19], v[164:165], v[106:107], v[18:19]
	v_pk_mul_f32 v[20:21], v[20:21], v[84:85]
	v_pk_fma_f32 v[20:21], v[166:167], v[108:109], v[20:21]
	v_pk_mul_f32 v[22:23], v[22:23], v[86:87]
	v_pk_fma_f32 v[22:23], v[168:169], v[110:111], v[22:23]
	v_pk_mul_f32 v[24:25], v[24:25], v[88:89]
	v_pk_fma_f32 v[24:25], v[170:171], v[112:113], v[24:25]
	v_pk_mul_f32 v[26:27], v[26:27], v[90:91]
	v_pk_fma_f32 v[26:27], v[172:173], v[114:115], v[26:27]
	v_pk_mul_f32 v[28:29], v[28:29], v[92:93]
	v_pk_fma_f32 v[28:29], v[174:175], v[116:117], v[28:29]
	v_pk_mul_f32 v[30:31], v[30:31], v[94:95]
	v_pk_fma_f32 v[30:31], v[176:177], v[118:119], v[30:31]
	v_pk_mul_f32 v[32:33], v[32:33], v[96:97]
	v_pk_fma_f32 v[32:33], v[178:179], v[120:121], v[32:33]
	s_waitcnt vmcnt(0)
	v_pk_mul_f32 v[2:3], v[2:3], v[82:83]
	v_pk_fma_f32 v[2:3], v[180:181], v[106:107], v[2:3]
	v_pk_mul_f32 v[4:5], v[4:5], v[84:85]
	v_pk_fma_f32 v[4:5], v[182:183], v[108:109], v[4:5]
	v_pk_mul_f32 v[6:7], v[6:7], v[86:87]
	v_pk_fma_f32 v[6:7], v[184:185], v[110:111], v[6:7]
	v_pk_mul_f32 v[8:9], v[8:9], v[88:89]
	v_pk_fma_f32 v[8:9], v[186:187], v[112:113], v[8:9]
	v_pk_mul_f32 v[10:11], v[10:11], v[90:91]
	v_pk_fma_f32 v[10:11], v[188:189], v[114:115], v[10:11]
	v_pk_mul_f32 v[12:13], v[12:13], v[92:93]
	v_pk_fma_f32 v[12:13], v[190:191], v[116:117], v[12:13]
	v_pk_mul_f32 v[14:15], v[14:15], v[94:95]
	v_pk_fma_f32 v[14:15], v[192:193], v[118:119], v[14:15]
	v_pk_mul_f32 v[16:17], v[16:17], v[96:97]
	v_pk_fma_f32 v[16:17], v[194:195], v[120:121], v[16:17]
	s_lshr_b32 s1, s1, 2
	s_bitcmp1_b32 s1, 0
	s_cbranch_scc0 .Lfa_epi_plain
	s_sub_u32 s12, s12, 0x4000
	s_subb_u32 s13, s13, 0
.Lfa_epi_pub:
	global_store_dwordx4 v66, v[50:53], s[12:13] offset:0 sc0 sc1
	global_store_dwordx4 v66, v[54:57], s[12:13] offset:1024 sc0 sc1
	global_store_dwordx4 v66, v[58:61], s[12:13] offset:2048 sc0 sc1
	global_store_dwordx4 v66, v[62:65], s[12:13] offset:3072 sc0 sc1
	s_add_u32 s12, s12, 0x1000
	s_addc_u32 s13, s13, 0
	global_store_dwordx4 v66, v[34:37], s[12:13] offset:0 sc0 sc1
	global_store_dwordx4 v66, v[38:41], s[12:13] offset:1024 sc0 sc1
	global_store_dwordx4 v66, v[42:45], s[12:13] offset:2048 sc0 sc1
	global_store_dwordx4 v66, v[46:49], s[12:13] offset:3072 sc0 sc1
	s_add_u32 s12, s12, 0x1000
	s_addc_u32 s13, s13, 0
	global_store_dwordx4 v66, v[18:21], s[12:13] offset:0 sc0 sc1
	global_store_dwordx4 v66, v[22:25], s[12:13] offset:1024 sc0 sc1
	global_store_dwordx4 v66, v[26:29], s[12:13] offset:2048 sc0 sc1
	global_store_dwordx4 v66, v[30:33], s[12:13] offset:3072 sc0 sc1
	s_add_u32 s12, s12, 0x1000
	s_addc_u32 s13, s13, 0
	global_store_dwordx4 v66, v[2:5], s[12:13] offset:0 sc0 sc1
	global_store_dwordx4 v66, v[6:9], s[12:13] offset:1024 sc0 sc1
	global_store_dwordx4 v66, v[10:13], s[12:13] offset:2048 sc0 sc1
	global_store_dwordx4 v66, v[14:17], s[12:13] offset:3072 sc0 sc1
	s_add_u32 s12, s12, 0x1000
	s_addc_u32 s13, s13, 0
	v_mov_b32_e32 v68, v196
	v_mov_b32_e32 v69, v0
	global_store_dwordx2 v67, v[68:69], s[14:15] sc0 sc1
	s_waitcnt vmcnt(0)
	v_mov_b32_e32 v68, s5
	global_store_dword v1, v68, s[18:19] sc0 sc1
	s_branch .Lfa_epi_end
